# k_rope skinny GEMM K-loop regenerated with 4 steps of loads in flight (was ~2)
# speedup vs baseline: 1.0004x; 1.0004x over previous
.LBB0_398:
	v_ashrrev_i32_e32 v137, 31, v136
	v_lshlrev_b64 v[138:139], 12, v[136:137]
	v_lshl_add_u64 v[248:249], v[0:1], 0, v[138:139]
	s_mov_b64 s[4:5], 0x20000
	v_lshl_add_u64 v[154:155], v[2:3], 0, s[4:5]
	v_lshlrev_b64 v[142:143], 8, v[136:137]
	v_lshl_add_u64 v[246:247], v[132:133], 0, v[142:143]
	global_load_dwordx4 v[146:149], v[246:247], off
	global_load_dwordx4 v[150:153], v[246:247], off offset:16
	s_addk_i32 s0, 0x400
	s_cmp_gt_i32 s0, -1
	global_load_dwordx4 v[4:7], v[248:249], off
	global_load_dwordx4 v[8:11], v[2:3], off
	global_load_dwordx4 v[12:15], v[154:155], off
	global_load_dwordx4 v[16:19], v[248:249], off offset:64
	global_load_dwordx4 v[20:23], v[2:3], off offset:64
	global_load_dwordx4 v[24:27], v[154:155], off offset:64
	global_load_dwordx4 v[28:31], v[248:249], off offset:128
	global_load_dwordx4 v[32:35], v[2:3], off offset:128
	global_load_dwordx4 v[36:39], v[154:155], off offset:128
	global_load_dwordx4 v[40:43], v[248:249], off offset:192
	global_load_dwordx4 v[44:47], v[2:3], off offset:192
	global_load_dwordx4 v[48:51], v[154:155], off offset:192
	global_load_dwordx4 v[52:55], v[248:249], off offset:256
	global_load_dwordx4 v[56:59], v[2:3], off offset:256
	global_load_dwordx4 v[60:63], v[154:155], off offset:256
	global_load_dwordx4 v[64:67], v[248:249], off offset:320
	global_load_dwordx4 v[68:71], v[2:3], off offset:320
	global_load_dwordx4 v[72:75], v[154:155], off offset:320
	global_load_dwordx4 v[76:79], v[248:249], off offset:384
	global_load_dwordx4 v[80:83], v[2:3], off offset:384
	global_load_dwordx4 v[84:87], v[154:155], off offset:384
	global_load_dwordx4 v[88:91], v[248:249], off offset:448
	global_load_dwordx4 v[92:95], v[2:3], off offset:448
	global_load_dwordx4 v[96:99], v[154:155], off offset:448
	global_load_dwordx4 v[100:103], v[248:249], off offset:512
	global_load_dwordx4 v[104:107], v[2:3], off offset:512
	global_load_dwordx4 v[108:111], v[154:155], off offset:512
	global_load_dwordx4 v[112:115], v[248:249], off offset:576
	global_load_dwordx4 v[116:119], v[2:3], off offset:576
	global_load_dwordx4 v[120:123], v[154:155], off offset:576
	global_load_dwordx4 v[124:127], v[248:249], off offset:640
	global_load_dwordx4 v[128:131], v[2:3], off offset:640
	global_load_dwordx4 v[156:159], v[154:155], off offset:640
	global_load_dwordx4 v[160:163], v[248:249], off offset:704
	global_load_dwordx4 v[164:167], v[2:3], off offset:704
	global_load_dwordx4 v[168:171], v[154:155], off offset:704
	global_load_dwordx4 v[172:175], v[248:249], off offset:768
	global_load_dwordx4 v[176:179], v[2:3], off offset:768
	global_load_dwordx4 v[180:183], v[154:155], off offset:768
	global_load_dwordx4 v[184:187], v[248:249], off offset:832
	global_load_dwordx4 v[188:191], v[2:3], off offset:832
	global_load_dwordx4 v[192:195], v[154:155], off offset:832
	global_load_dwordx4 v[196:199], v[248:249], off offset:896
	global_load_dwordx4 v[200:203], v[2:3], off offset:896
	global_load_dwordx4 v[204:207], v[154:155], off offset:896
	global_load_dwordx4 v[208:211], v[248:249], off offset:960
	global_load_dwordx4 v[212:215], v[2:3], off offset:960
	global_load_dwordx4 v[216:219], v[154:155], off offset:960
	s_waitcnt vmcnt(45)
	v_mfma_f32_16x16x32_bf16 v[138:141], v[8:11], v[4:7], 0
	v_mfma_f32_16x16x32_bf16 v[142:145], v[12:15], v[4:7], 0
	s_waitcnt vmcnt(42)
	v_mfma_f32_16x16x32_bf16 v[138:141], v[20:23], v[16:19], v[138:141]
	v_mfma_f32_16x16x32_bf16 v[142:145], v[24:27], v[16:19], v[142:145]
	s_waitcnt vmcnt(39)
	v_mfma_f32_16x16x32_bf16 v[138:141], v[32:35], v[28:31], v[138:141]
	v_mfma_f32_16x16x32_bf16 v[142:145], v[36:39], v[28:31], v[142:145]
	s_waitcnt vmcnt(36)
	v_mfma_f32_16x16x32_bf16 v[138:141], v[44:47], v[40:43], v[138:141]
	v_mfma_f32_16x16x32_bf16 v[142:145], v[48:51], v[40:43], v[142:145]
	global_load_dwordx4 v[4:7], v[248:249], off offset:1024
	global_load_dwordx4 v[8:11], v[2:3], off offset:1024
	global_load_dwordx4 v[12:15], v[154:155], off offset:1024
	global_load_dwordx4 v[16:19], v[248:249], off offset:1088
	global_load_dwordx4 v[20:23], v[2:3], off offset:1088
	global_load_dwordx4 v[24:27], v[154:155], off offset:1088
	global_load_dwordx4 v[28:31], v[248:249], off offset:1152
	global_load_dwordx4 v[32:35], v[2:3], off offset:1152
	global_load_dwordx4 v[36:39], v[154:155], off offset:1152
	global_load_dwordx4 v[40:43], v[248:249], off offset:1216
	global_load_dwordx4 v[44:47], v[2:3], off offset:1216
	global_load_dwordx4 v[48:51], v[154:155], off offset:1216
	s_waitcnt vmcnt(45)
	v_mfma_f32_16x16x32_bf16 v[138:141], v[56:59], v[52:55], v[138:141]
	v_mfma_f32_16x16x32_bf16 v[142:145], v[60:63], v[52:55], v[142:145]
	s_waitcnt vmcnt(42)
	v_mfma_f32_16x16x32_bf16 v[138:141], v[68:71], v[64:67], v[138:141]
	v_mfma_f32_16x16x32_bf16 v[142:145], v[72:75], v[64:67], v[142:145]
	s_waitcnt vmcnt(39)
	v_mfma_f32_16x16x32_bf16 v[138:141], v[80:83], v[76:79], v[138:141]
	v_mfma_f32_16x16x32_bf16 v[142:145], v[84:87], v[76:79], v[142:145]
	s_waitcnt vmcnt(36)
	v_mfma_f32_16x16x32_bf16 v[138:141], v[92:95], v[88:91], v[138:141]
	v_mfma_f32_16x16x32_bf16 v[142:145], v[96:99], v[88:91], v[142:145]
	global_load_dwordx4 v[52:55], v[248:249], off offset:1280
	global_load_dwordx4 v[56:59], v[2:3], off offset:1280
	global_load_dwordx4 v[60:63], v[154:155], off offset:1280
	global_load_dwordx4 v[64:67], v[248:249], off offset:1344
	global_load_dwordx4 v[68:71], v[2:3], off offset:1344
	global_load_dwordx4 v[72:75], v[154:155], off offset:1344
	global_load_dwordx4 v[76:79], v[248:249], off offset:1408
	global_load_dwordx4 v[80:83], v[2:3], off offset:1408
	global_load_dwordx4 v[84:87], v[154:155], off offset:1408
	global_load_dwordx4 v[88:91], v[248:249], off offset:1472
	global_load_dwordx4 v[92:95], v[2:3], off offset:1472
	global_load_dwordx4 v[96:99], v[154:155], off offset:1472
	s_waitcnt vmcnt(45)
	v_mfma_f32_16x16x32_bf16 v[138:141], v[104:107], v[100:103], v[138:141]
	v_mfma_f32_16x16x32_bf16 v[142:145], v[108:111], v[100:103], v[142:145]
	s_waitcnt vmcnt(42)
	v_mfma_f32_16x16x32_bf16 v[138:141], v[116:119], v[112:115], v[138:141]
	v_mfma_f32_16x16x32_bf16 v[142:145], v[120:123], v[112:115], v[142:145]
	s_waitcnt vmcnt(39)
	v_mfma_f32_16x16x32_bf16 v[138:141], v[128:131], v[124:127], v[138:141]
	v_mfma_f32_16x16x32_bf16 v[142:145], v[156:159], v[124:127], v[142:145]
	s_waitcnt vmcnt(36)
	v_mfma_f32_16x16x32_bf16 v[138:141], v[164:167], v[160:163], v[138:141]
	v_mfma_f32_16x16x32_bf16 v[142:145], v[168:171], v[160:163], v[142:145]
	global_load_dwordx4 v[100:103], v[248:249], off offset:1536
	global_load_dwordx4 v[104:107], v[2:3], off offset:1536
	global_load_dwordx4 v[108:111], v[154:155], off offset:1536
	global_load_dwordx4 v[112:115], v[248:249], off offset:1600
	global_load_dwordx4 v[116:119], v[2:3], off offset:1600
	global_load_dwordx4 v[120:123], v[154:155], off offset:1600
	global_load_dwordx4 v[124:127], v[248:249], off offset:1664
	global_load_dwordx4 v[128:131], v[2:3], off offset:1664
	global_load_dwordx4 v[156:159], v[154:155], off offset:1664
	global_load_dwordx4 v[160:163], v[248:249], off offset:1728
	global_load_dwordx4 v[164:167], v[2:3], off offset:1728
	global_load_dwordx4 v[168:171], v[154:155], off offset:1728
	s_waitcnt vmcnt(45)
	v_mfma_f32_16x16x32_bf16 v[138:141], v[176:179], v[172:175], v[138:141]
	v_mfma_f32_16x16x32_bf16 v[142:145], v[180:183], v[172:175], v[142:145]
	s_waitcnt vmcnt(42)
	v_mfma_f32_16x16x32_bf16 v[138:141], v[188:191], v[184:187], v[138:141]
	v_mfma_f32_16x16x32_bf16 v[142:145], v[192:195], v[184:187], v[142:145]
	s_waitcnt vmcnt(39)
	v_mfma_f32_16x16x32_bf16 v[138:141], v[200:203], v[196:199], v[138:141]
	v_mfma_f32_16x16x32_bf16 v[142:145], v[204:207], v[196:199], v[142:145]
	s_waitcnt vmcnt(36)
	v_mfma_f32_16x16x32_bf16 v[138:141], v[212:215], v[208:211], v[138:141]
	v_mfma_f32_16x16x32_bf16 v[142:145], v[216:219], v[208:211], v[142:145]
	global_load_dwordx4 v[172:175], v[248:249], off offset:1792
	global_load_dwordx4 v[176:179], v[2:3], off offset:1792
	global_load_dwordx4 v[180:183], v[154:155], off offset:1792
	global_load_dwordx4 v[184:187], v[248:249], off offset:1856
	global_load_dwordx4 v[188:191], v[2:3], off offset:1856
	global_load_dwordx4 v[192:195], v[154:155], off offset:1856
	global_load_dwordx4 v[196:199], v[248:249], off offset:1920
	global_load_dwordx4 v[200:203], v[2:3], off offset:1920
	global_load_dwordx4 v[204:207], v[154:155], off offset:1920
	global_load_dwordx4 v[208:211], v[248:249], off offset:1984
	global_load_dwordx4 v[212:215], v[2:3], off offset:1984
	global_load_dwordx4 v[216:219], v[154:155], off offset:1984
	s_waitcnt vmcnt(45)
	v_mfma_f32_16x16x32_bf16 v[138:141], v[8:11], v[4:7], v[138:141]
	v_mfma_f32_16x16x32_bf16 v[142:145], v[12:15], v[4:7], v[142:145]
	s_waitcnt vmcnt(42)
	v_mfma_f32_16x16x32_bf16 v[138:141], v[20:23], v[16:19], v[138:141]
	v_mfma_f32_16x16x32_bf16 v[142:145], v[24:27], v[16:19], v[142:145]
	s_waitcnt vmcnt(39)
	v_mfma_f32_16x16x32_bf16 v[138:141], v[32:35], v[28:31], v[138:141]
	v_mfma_f32_16x16x32_bf16 v[142:145], v[36:39], v[28:31], v[142:145]
	s_waitcnt vmcnt(36)
	v_mfma_f32_16x16x32_bf16 v[138:141], v[44:47], v[40:43], v[138:141]
	v_mfma_f32_16x16x32_bf16 v[142:145], v[48:51], v[40:43], v[142:145]
	global_load_dwordx4 v[4:7], v[248:249], off offset:2048
	global_load_dwordx4 v[8:11], v[2:3], off offset:2048
	global_load_dwordx4 v[12:15], v[154:155], off offset:2048
	global_load_dwordx4 v[16:19], v[248:249], off offset:2112
	global_load_dwordx4 v[20:23], v[2:3], off offset:2112
	global_load_dwordx4 v[24:27], v[154:155], off offset:2112
	global_load_dwordx4 v[28:31], v[248:249], off offset:2176
	global_load_dwordx4 v[32:35], v[2:3], off offset:2176
	global_load_dwordx4 v[36:39], v[154:155], off offset:2176
	global_load_dwordx4 v[40:43], v[248:249], off offset:2240
	global_load_dwordx4 v[44:47], v[2:3], off offset:2240
	global_load_dwordx4 v[48:51], v[154:155], off offset:2240
	s_waitcnt vmcnt(45)
	v_mfma_f32_16x16x32_bf16 v[138:141], v[56:59], v[52:55], v[138:141]
	v_mfma_f32_16x16x32_bf16 v[142:145], v[60:63], v[52:55], v[142:145]
	s_waitcnt vmcnt(42)
	v_mfma_f32_16x16x32_bf16 v[138:141], v[68:71], v[64:67], v[138:141]
	v_mfma_f32_16x16x32_bf16 v[142:145], v[72:75], v[64:67], v[142:145]
	s_waitcnt vmcnt(39)
	v_mfma_f32_16x16x32_bf16 v[138:141], v[80:83], v[76:79], v[138:141]
	v_mfma_f32_16x16x32_bf16 v[142:145], v[84:87], v[76:79], v[142:145]
	s_waitcnt vmcnt(36)
	v_mfma_f32_16x16x32_bf16 v[138:141], v[92:95], v[88:91], v[138:141]
	v_mfma_f32_16x16x32_bf16 v[142:145], v[96:99], v[88:91], v[142:145]
	global_load_dwordx4 v[52:55], v[248:249], off offset:2304
	global_load_dwordx4 v[56:59], v[2:3], off offset:2304
	global_load_dwordx4 v[60:63], v[154:155], off offset:2304
	global_load_dwordx4 v[64:67], v[248:249], off offset:2368
	global_load_dwordx4 v[68:71], v[2:3], off offset:2368
	global_load_dwordx4 v[72:75], v[154:155], off offset:2368
	global_load_dwordx4 v[76:79], v[248:249], off offset:2432
	global_load_dwordx4 v[80:83], v[2:3], off offset:2432
	global_load_dwordx4 v[84:87], v[154:155], off offset:2432
	global_load_dwordx4 v[88:91], v[248:249], off offset:2496
	global_load_dwordx4 v[92:95], v[2:3], off offset:2496
	global_load_dwordx4 v[96:99], v[154:155], off offset:2496
	s_waitcnt vmcnt(45)
	v_mfma_f32_16x16x32_bf16 v[138:141], v[104:107], v[100:103], v[138:141]
	v_mfma_f32_16x16x32_bf16 v[142:145], v[108:111], v[100:103], v[142:145]
	s_waitcnt vmcnt(42)
	v_mfma_f32_16x16x32_bf16 v[138:141], v[116:119], v[112:115], v[138:141]
	v_mfma_f32_16x16x32_bf16 v[142:145], v[120:123], v[112:115], v[142:145]
	s_waitcnt vmcnt(39)
	v_mfma_f32_16x16x32_bf16 v[138:141], v[128:131], v[124:127], v[138:141]
	v_mfma_f32_16x16x32_bf16 v[142:145], v[156:159], v[124:127], v[142:145]
	s_waitcnt vmcnt(36)
	v_mfma_f32_16x16x32_bf16 v[138:141], v[164:167], v[160:163], v[138:141]
	v_mfma_f32_16x16x32_bf16 v[142:145], v[168:171], v[160:163], v[142:145]
	global_load_dwordx4 v[100:103], v[248:249], off offset:2560
	global_load_dwordx4 v[104:107], v[2:3], off offset:2560
	global_load_dwordx4 v[108:111], v[154:155], off offset:2560
	global_load_dwordx4 v[112:115], v[248:249], off offset:2624
	global_load_dwordx4 v[116:119], v[2:3], off offset:2624
	global_load_dwordx4 v[120:123], v[154:155], off offset:2624
	global_load_dwordx4 v[124:127], v[248:249], off offset:2688
	global_load_dwordx4 v[128:131], v[2:3], off offset:2688
	global_load_dwordx4 v[156:159], v[154:155], off offset:2688
	global_load_dwordx4 v[160:163], v[248:249], off offset:2752
	global_load_dwordx4 v[164:167], v[2:3], off offset:2752
	global_load_dwordx4 v[168:171], v[154:155], off offset:2752
	s_waitcnt vmcnt(45)
	v_mfma_f32_16x16x32_bf16 v[138:141], v[176:179], v[172:175], v[138:141]
	v_mfma_f32_16x16x32_bf16 v[142:145], v[180:183], v[172:175], v[142:145]
	s_waitcnt vmcnt(42)
	v_mfma_f32_16x16x32_bf16 v[138:141], v[188:191], v[184:187], v[138:141]
	v_mfma_f32_16x16x32_bf16 v[142:145], v[192:195], v[184:187], v[142:145]
	s_waitcnt vmcnt(39)
	v_mfma_f32_16x16x32_bf16 v[138:141], v[200:203], v[196:199], v[138:141]
	v_mfma_f32_16x16x32_bf16 v[142:145], v[204:207], v[196:199], v[142:145]
	s_waitcnt vmcnt(36)
	v_mfma_f32_16x16x32_bf16 v[138:141], v[212:215], v[208:211], v[138:141]
	v_mfma_f32_16x16x32_bf16 v[142:145], v[216:219], v[208:211], v[142:145]
	global_load_dwordx4 v[172:175], v[248:249], off offset:2816
	global_load_dwordx4 v[176:179], v[2:3], off offset:2816
	global_load_dwordx4 v[180:183], v[154:155], off offset:2816
	global_load_dwordx4 v[184:187], v[248:249], off offset:2880
	global_load_dwordx4 v[188:191], v[2:3], off offset:2880
	global_load_dwordx4 v[192:195], v[154:155], off offset:2880
	global_load_dwordx4 v[196:199], v[248:249], off offset:2944
	global_load_dwordx4 v[200:203], v[2:3], off offset:2944
	global_load_dwordx4 v[204:207], v[154:155], off offset:2944
	global_load_dwordx4 v[208:211], v[248:249], off offset:3008
	global_load_dwordx4 v[212:215], v[2:3], off offset:3008
	global_load_dwordx4 v[216:219], v[154:155], off offset:3008
	s_waitcnt vmcnt(45)
	v_mfma_f32_16x16x32_bf16 v[138:141], v[8:11], v[4:7], v[138:141]
	v_mfma_f32_16x16x32_bf16 v[142:145], v[12:15], v[4:7], v[142:145]
	s_waitcnt vmcnt(42)
	v_mfma_f32_16x16x32_bf16 v[138:141], v[20:23], v[16:19], v[138:141]
	v_mfma_f32_16x16x32_bf16 v[142:145], v[24:27], v[16:19], v[142:145]
	s_waitcnt vmcnt(39)
	v_mfma_f32_16x16x32_bf16 v[138:141], v[32:35], v[28:31], v[138:141]
	v_mfma_f32_16x16x32_bf16 v[142:145], v[36:39], v[28:31], v[142:145]
	s_waitcnt vmcnt(36)
	v_mfma_f32_16x16x32_bf16 v[138:141], v[44:47], v[40:43], v[138:141]
	v_mfma_f32_16x16x32_bf16 v[142:145], v[48:51], v[40:43], v[142:145]
	global_load_dwordx4 v[4:7], v[248:249], off offset:3072
	global_load_dwordx4 v[8:11], v[2:3], off offset:3072
	global_load_dwordx4 v[12:15], v[154:155], off offset:3072
	global_load_dwordx4 v[16:19], v[248:249], off offset:3136
	global_load_dwordx4 v[20:23], v[2:3], off offset:3136
	global_load_dwordx4 v[24:27], v[154:155], off offset:3136
	global_load_dwordx4 v[28:31], v[248:249], off offset:3200
	global_load_dwordx4 v[32:35], v[2:3], off offset:3200
	global_load_dwordx4 v[36:39], v[154:155], off offset:3200
	global_load_dwordx4 v[40:43], v[248:249], off offset:3264
	global_load_dwordx4 v[44:47], v[2:3], off offset:3264
	global_load_dwordx4 v[48:51], v[154:155], off offset:3264
	s_waitcnt vmcnt(45)
	v_mfma_f32_16x16x32_bf16 v[138:141], v[56:59], v[52:55], v[138:141]
	v_mfma_f32_16x16x32_bf16 v[142:145], v[60:63], v[52:55], v[142:145]
	s_waitcnt vmcnt(42)
	v_mfma_f32_16x16x32_bf16 v[138:141], v[68:71], v[64:67], v[138:141]
	v_mfma_f32_16x16x32_bf16 v[142:145], v[72:75], v[64:67], v[142:145]
	s_waitcnt vmcnt(39)
	v_mfma_f32_16x16x32_bf16 v[138:141], v[80:83], v[76:79], v[138:141]
	v_mfma_f32_16x16x32_bf16 v[142:145], v[84:87], v[76:79], v[142:145]
	s_waitcnt vmcnt(36)
	v_mfma_f32_16x16x32_bf16 v[138:141], v[92:95], v[88:91], v[138:141]
	v_mfma_f32_16x16x32_bf16 v[142:145], v[96:99], v[88:91], v[142:145]
	global_load_dwordx4 v[52:55], v[248:249], off offset:3328
	global_load_dwordx4 v[56:59], v[2:3], off offset:3328
	global_load_dwordx4 v[60:63], v[154:155], off offset:3328
	global_load_dwordx4 v[64:67], v[248:249], off offset:3392
	global_load_dwordx4 v[68:71], v[2:3], off offset:3392
	global_load_dwordx4 v[72:75], v[154:155], off offset:3392
	global_load_dwordx4 v[76:79], v[248:249], off offset:3456
	global_load_dwordx4 v[80:83], v[2:3], off offset:3456
	global_load_dwordx4 v[84:87], v[154:155], off offset:3456
	global_load_dwordx4 v[88:91], v[248:249], off offset:3520
	global_load_dwordx4 v[92:95], v[2:3], off offset:3520
	global_load_dwordx4 v[96:99], v[154:155], off offset:3520
	s_waitcnt vmcnt(45)
	v_mfma_f32_16x16x32_bf16 v[138:141], v[104:107], v[100:103], v[138:141]
	v_mfma_f32_16x16x32_bf16 v[142:145], v[108:111], v[100:103], v[142:145]
	s_waitcnt vmcnt(42)
	v_mfma_f32_16x16x32_bf16 v[138:141], v[116:119], v[112:115], v[138:141]
	v_mfma_f32_16x16x32_bf16 v[142:145], v[120:123], v[112:115], v[142:145]
	s_waitcnt vmcnt(39)
	v_mfma_f32_16x16x32_bf16 v[138:141], v[128:131], v[124:127], v[138:141]
	v_mfma_f32_16x16x32_bf16 v[142:145], v[156:159], v[124:127], v[142:145]
	s_waitcnt vmcnt(36)
	v_mfma_f32_16x16x32_bf16 v[138:141], v[164:167], v[160:163], v[138:141]
	v_mfma_f32_16x16x32_bf16 v[142:145], v[168:171], v[160:163], v[142:145]
	global_load_dwordx4 v[100:103], v[248:249], off offset:3584
	global_load_dwordx4 v[104:107], v[2:3], off offset:3584
	global_load_dwordx4 v[108:111], v[154:155], off offset:3584
	global_load_dwordx4 v[112:115], v[248:249], off offset:3648
	global_load_dwordx4 v[116:119], v[2:3], off offset:3648
	global_load_dwordx4 v[120:123], v[154:155], off offset:3648
	global_load_dwordx4 v[124:127], v[248:249], off offset:3712
	global_load_dwordx4 v[128:131], v[2:3], off offset:3712
	global_load_dwordx4 v[156:159], v[154:155], off offset:3712
	global_load_dwordx4 v[160:163], v[248:249], off offset:3776
	global_load_dwordx4 v[164:167], v[2:3], off offset:3776
	global_load_dwordx4 v[168:171], v[154:155], off offset:3776
	s_waitcnt vmcnt(45)
	v_mfma_f32_16x16x32_bf16 v[138:141], v[176:179], v[172:175], v[138:141]
	v_mfma_f32_16x16x32_bf16 v[142:145], v[180:183], v[172:175], v[142:145]
	s_waitcnt vmcnt(42)
	v_mfma_f32_16x16x32_bf16 v[138:141], v[188:191], v[184:187], v[138:141]
	v_mfma_f32_16x16x32_bf16 v[142:145], v[192:195], v[184:187], v[142:145]
	s_waitcnt vmcnt(39)
	v_mfma_f32_16x16x32_bf16 v[138:141], v[200:203], v[196:199], v[138:141]
	v_mfma_f32_16x16x32_bf16 v[142:145], v[204:207], v[196:199], v[142:145]
	s_waitcnt vmcnt(36)
	v_mfma_f32_16x16x32_bf16 v[138:141], v[212:215], v[208:211], v[138:141]
	v_mfma_f32_16x16x32_bf16 v[142:145], v[216:219], v[208:211], v[142:145]
	global_load_dwordx4 v[172:175], v[248:249], off offset:3840
	global_load_dwordx4 v[176:179], v[2:3], off offset:3840
	global_load_dwordx4 v[180:183], v[154:155], off offset:3840
	global_load_dwordx4 v[184:187], v[248:249], off offset:3904
	global_load_dwordx4 v[188:191], v[2:3], off offset:3904
	global_load_dwordx4 v[192:195], v[154:155], off offset:3904
	global_load_dwordx4 v[196:199], v[248:249], off offset:3968
	global_load_dwordx4 v[200:203], v[2:3], off offset:3968
	global_load_dwordx4 v[204:207], v[154:155], off offset:3968
	global_load_dwordx4 v[208:211], v[248:249], off offset:4032
	global_load_dwordx4 v[212:215], v[2:3], off offset:4032
	global_load_dwordx4 v[216:219], v[154:155], off offset:4032
	s_waitcnt vmcnt(45)
	v_mfma_f32_16x16x32_bf16 v[138:141], v[8:11], v[4:7], v[138:141]
	v_mfma_f32_16x16x32_bf16 v[142:145], v[12:15], v[4:7], v[142:145]
	s_waitcnt vmcnt(42)
	v_mfma_f32_16x16x32_bf16 v[138:141], v[20:23], v[16:19], v[138:141]
	v_mfma_f32_16x16x32_bf16 v[142:145], v[24:27], v[16:19], v[142:145]
	s_waitcnt vmcnt(39)
	v_mfma_f32_16x16x32_bf16 v[138:141], v[32:35], v[28:31], v[138:141]
	v_mfma_f32_16x16x32_bf16 v[142:145], v[36:39], v[28:31], v[142:145]
	s_waitcnt vmcnt(36)
	v_mfma_f32_16x16x32_bf16 v[138:141], v[44:47], v[40:43], v[138:141]
	v_mfma_f32_16x16x32_bf16 v[142:145], v[48:51], v[40:43], v[142:145]
	s_waitcnt vmcnt(33)
	v_mfma_f32_16x16x32_bf16 v[138:141], v[56:59], v[52:55], v[138:141]
	v_mfma_f32_16x16x32_bf16 v[142:145], v[60:63], v[52:55], v[142:145]
	s_waitcnt vmcnt(30)
	v_mfma_f32_16x16x32_bf16 v[138:141], v[68:71], v[64:67], v[138:141]
	v_mfma_f32_16x16x32_bf16 v[142:145], v[72:75], v[64:67], v[142:145]
	s_waitcnt vmcnt(27)
	v_mfma_f32_16x16x32_bf16 v[138:141], v[80:83], v[76:79], v[138:141]
	v_mfma_f32_16x16x32_bf16 v[142:145], v[84:87], v[76:79], v[142:145]
	s_waitcnt vmcnt(24)
	v_mfma_f32_16x16x32_bf16 v[138:141], v[92:95], v[88:91], v[138:141]
	v_mfma_f32_16x16x32_bf16 v[142:145], v[96:99], v[88:91], v[142:145]
	s_waitcnt vmcnt(21)
	v_mfma_f32_16x16x32_bf16 v[138:141], v[104:107], v[100:103], v[138:141]
	v_mfma_f32_16x16x32_bf16 v[142:145], v[108:111], v[100:103], v[142:145]
	s_waitcnt vmcnt(18)
	v_mfma_f32_16x16x32_bf16 v[138:141], v[116:119], v[112:115], v[138:141]
	v_mfma_f32_16x16x32_bf16 v[142:145], v[120:123], v[112:115], v[142:145]
	s_waitcnt vmcnt(15)
	v_mfma_f32_16x16x32_bf16 v[138:141], v[128:131], v[124:127], v[138:141]
	v_mfma_f32_16x16x32_bf16 v[142:145], v[156:159], v[124:127], v[142:145]
	s_waitcnt vmcnt(12)
	v_mfma_f32_16x16x32_bf16 v[138:141], v[164:167], v[160:163], v[138:141]
	v_mfma_f32_16x16x32_bf16 v[142:145], v[168:171], v[160:163], v[142:145]
	s_waitcnt vmcnt(9)
	v_mfma_f32_16x16x32_bf16 v[138:141], v[176:179], v[172:175], v[138:141]
	v_mfma_f32_16x16x32_bf16 v[142:145], v[180:183], v[172:175], v[142:145]
	s_waitcnt vmcnt(6)
	v_mfma_f32_16x16x32_bf16 v[138:141], v[188:191], v[184:187], v[138:141]
	v_mfma_f32_16x16x32_bf16 v[142:145], v[192:195], v[184:187], v[142:145]
	s_waitcnt vmcnt(3)
	v_mfma_f32_16x16x32_bf16 v[138:141], v[200:203], v[196:199], v[138:141]
	v_mfma_f32_16x16x32_bf16 v[142:145], v[204:207], v[196:199], v[142:145]
	s_waitcnt vmcnt(0)
	v_mfma_f32_16x16x32_bf16 v[138:141], v[212:215], v[208:211], v[138:141]
	v_mfma_f32_16x16x32_bf16 v[142:145], v[216:219], v[208:211], v[142:145]
	s_nop 7
	s_nop 3
	v_mov_b32_e32 v154, v138
	v_mov_b32_e32 v155, v142
	s_waitcnt vmcnt(0)
	v_pk_mul_f32 v[154:155], v[154:155], v[146:147]
	s_nop 0
	v_sub_f32_e32 v156, v154, v155
	v_mov_b32_e32 v154, v142
	v_mov_b32_e32 v155, v138
	v_pk_mul_f32 v[146:147], v[154:155], v[146:147]
	v_mov_b32_e32 v142, v139
	v_add_f32_e32 v138, v146, v147
	v_cvt_pk_bf16_f32 v146, v156, v138
	v_mov_b32_e32 v138, v143
	v_pk_mul_f32 v[138:139], v[138:139], v[148:149]
	v_pk_mul_f32 v[154:155], v[142:143], v[148:149]
	v_add_f32_e32 v138, v138, v139
	v_sub_f32_e32 v142, v154, v155
	v_cvt_pk_bf16_f32 v147, v142, v138
	v_mov_b32_e32 v138, v140
	v_mov_b32_e32 v139, v144
	s_waitcnt vmcnt(0)
	v_pk_mul_f32 v[138:139], v[138:139], v[150:151]
	s_nop 0
	v_sub_f32_e32 v142, v138, v139
	v_mov_b32_e32 v138, v144
	v_mov_b32_e32 v139, v140
	v_pk_mul_f32 v[138:139], v[138:139], v[150:151]
	v_mov_b32_e32 v144, v141
	v_add_f32_e32 v138, v138, v139
	v_cvt_pk_bf16_f32 v148, v142, v138
	v_pk_mul_f32 v[138:139], v[144:145], v[152:153]
	v_mov_b32_e32 v140, v145
	v_sub_f32_e32 v142, v138, v139
	v_pk_mul_f32 v[138:139], v[140:141], v[152:153]
	s_nop 0
	v_add_f32_e32 v138, v138, v139
	v_cvt_pk_bf16_f32 v149, v142, v138
	v_lshlrev_b64 v[138:139], 7, v[136:137]
	v_lshl_add_u64 v[138:139], v[134:135], 0, v[138:139]
	v_add_u32_e32 v136, 0x4000, v136
	global_store_dwordx4 v[138:139], v[146:149], off
	s_cbranch_scc0 .LBB0_398
